# SSD decay-mask arithmetic between the barriers with packed f32 ops (22 -> 16 VALU per block), on top of the combination
# baseline (speedup 1.0000x reference)
.LBB0_347:
	s_or_b64 exec, exec, s[0:1]
	v_mul_f32_e32 v4, 0x3fb8aa3b, v4
	v_exp_f32_e32 v63, v4
	v_cmp_gt_i32_e64 s[38:39], s35, v1
	v_add_u32_e32 v4, 0xffffff00, v1
	v_mov_b32_e32 v5, 0x1000
	v_cndmask_b32_e64 v51, v4, v1, s[38:39]
	v_mov_b32_e32 v4, 0x1200
	s_lshl_b32 s0, s36, 4
	v_cndmask_b32_e64 v4, v4, v5, s[38:39]
	s_and_b32 s0, s0, 0x180
	v_ashrrev_i32_e32 v48, 4, v51
	v_or_b32_e32 v54, s0, v4
	v_lshlrev_b32_e32 v4, 3, v51
	s_movk_i32 s0, 0x78
	s_lshl_b32 s23, s36, 6
	s_lshl_b32 s85, s37, 12
	v_and_or_b32 v4, v4, s0, v54
	s_bitset1_b32 s23, 11
	v_lshlrev_b32_e32 v50, 2, v48
	s_add_i32 s70, s85, -16
	v_and_or_b32 v20, v2, 60, s23
	v_subrev_u32_e32 v5, 48, v50
	v_lshlrev_b32_e32 v2, 1, v4
	v_cmp_lt_i32_e32 vcc, 15, v48
	v_mov_b32_e32 v52, s70
	v_lshl_add_u64 v[22:23], s[96:97], 0, v[2:3]
	v_max_i32_e32 v2, 0, v5
	v_cndmask_b32_e32 v4, v229, v52, vcc
	v_add_u32_e32 v2, v2, v4
	v_mad_i64_i32 v[4:5], s[0:1], v2, s29, v[22:23]
	v_subrev_u32_e32 v2, 47, v50
	v_cmp_lt_i32_e32 vcc, 15, v2
	v_max_i32_e32 v8, 0, v2
	v_ashrrev_i32_e32 v49, 4, v1
	v_cndmask_b32_e32 v2, v229, v52, vcc
	v_add_u32_e32 v2, v2, v8
	v_mad_i64_i32 v[8:9], s[26:27], v2, s29, v[22:23]
	v_subrev_u32_e32 v2, 46, v50
	v_cmp_lt_i32_e32 vcc, 15, v2
	v_max_i32_e32 v12, 0, v2
	v_lshlrev_b32_e32 v55, 1, v49
	v_cndmask_b32_e32 v2, v229, v52, vcc
	v_add_u32_e32 v2, v2, v12
	v_mad_i64_i32 v[12:13], s[26:27], v2, s29, v[22:23]
	v_subrev_u32_e32 v2, 45, v50
	v_cmp_lt_i32_e32 vcc, 15, v2
	v_max_i32_e32 v16, 0, v2
	v_subrev_u32_e32 v21, 48, v55
	v_cndmask_b32_e32 v2, v229, v52, vcc
	v_add_u32_e32 v2, v2, v16
	v_mad_i64_i32 v[16:17], s[26:27], v2, s29, v[22:23]
	v_lshlrev_b32_e32 v2, 1, v20
	v_cmp_lt_i32_e32 vcc, 31, v49
	v_lshl_add_u64 v[46:47], s[96:97], 0, v[2:3]
	v_max_i32_e32 v2, 0, v21
	v_cndmask_b32_e32 v20, v229, v52, vcc
	v_add_u32_e32 v2, v2, v20
	v_mad_i64_i32 v[20:21], s[26:27], v2, s29, v[46:47]
	v_subrev_u32_e32 v2, 47, v55
	v_cmp_lt_i32_e32 vcc, 15, v2
	global_load_dwordx2 v[40:41], v[20:21], off
	v_max_i32_e32 v20, 0, v2
	v_cndmask_b32_e32 v2, v229, v52, vcc
	v_and_b32_e32 v65, 63, v1
	v_add_u32_e32 v2, v2, v20
	v_mad_i64_i32 v[20:21], s[26:27], v2, s29, v[46:47]
	v_max_u32_e32 v2, 48, v65
	v_readlane_b32 s42, v252, 52
	v_lshlrev_b32_e32 v2, 7, v2
	v_readlane_b32 s43, v252, 53
	global_load_dwordx2 v[42:43], v[20:21], off
	s_mov_b32 s24, 0x3fe000
	v_lshl_add_u64 v[20:21], s[42:43], 0, v[2:3]
	v_lshl_add_u64 v[20:21], v[20:21], 0, s[72:73]
	v_add_co_u32_e32 v20, vcc, s24, v20
	v_add_u32_e32 v2, 16, v50
	s_nop 0
	v_addc_co_u32_e32 v21, vcc, 0, v21, vcc
	v_cmp_lt_i32_e32 vcc, -1, v48
	global_load_dword v20, v[20:21], off offset:2048
	v_max_i32_e32 v2, 0, v2
	v_cndmask_b32_e32 v21, v229, v52, vcc
	v_add_u32_e32 v2, v2, v21
	v_mad_i64_i32 v[24:25], s[26:27], v2, s29, v[22:23]
	v_add_u32_e32 v2, 17, v50
	v_cmp_lt_i32_e32 vcc, 15, v2
	v_max_i32_e32 v21, 0, v2
	global_load_dwordx4 v[24:27], v[24:25], off
	v_cndmask_b32_e32 v2, v229, v52, vcc
	v_add_u32_e32 v2, v2, v21
	v_mad_i64_i32 v[28:29], s[26:27], v2, s29, v[22:23]
	v_add_u32_e32 v2, 18, v50
	v_cmp_lt_i32_e32 vcc, 15, v2
	v_max_i32_e32 v21, 0, v2
	s_ashr_i32 s21, s25, 8
	v_cndmask_b32_e32 v2, v229, v52, vcc
	v_add_u32_e32 v2, v2, v21
	v_mad_i64_i32 v[32:33], s[26:27], v2, s29, v[22:23]
	v_add_u32_e32 v2, 19, v50
	v_cmp_lt_i32_e32 vcc, 15, v2
	v_max_i32_e32 v21, 0, v2
	global_load_dwordx4 v[28:31], v[28:29], off
	v_cndmask_b32_e32 v2, v229, v52, vcc
	v_add_u32_e32 v2, v2, v21
	v_mad_i64_i32 v[22:23], s[26:27], v2, s29, v[22:23]
	v_add_u32_e32 v2, 16, v55
	v_cmp_lt_i32_e32 vcc, -1, v49
	v_max_i32_e32 v2, 0, v2
	global_load_dwordx4 v[36:39], v[22:23], off
	v_cndmask_b32_e32 v21, v229, v52, vcc
	v_add_u32_e32 v2, v2, v21
	v_mad_i64_i32 v[22:23], s[26:27], v2, s29, v[46:47]
	v_add_u32_e32 v2, 17, v55
	v_cmp_lt_i32_e32 vcc, 15, v2
	v_max_i32_e32 v21, 0, v2
	global_load_dwordx2 v[44:45], v[22:23], off
	v_cndmask_b32_e32 v2, v229, v52, vcc
	v_add_u32_e32 v2, v2, v21
	v_mad_i64_i32 v[22:23], s[26:27], v2, s29, v[46:47]
	v_or_b32_e32 v56, s85, v65
	s_lshr_b32 s22, s25, 6
	s_bfe_u32 s20, s25, 0x20006
	v_ashrrev_i32_e32 v57, 31, v56
	s_lshl_b32 s24, s21, 5
	s_sub_i32 s37, s85, 64
	s_lshl_b32 s26, s36, 7
	global_load_dwordx4 v[32:35], v[32:33], off
	s_add_u32 s36, s96, s26
	global_load_dwordx2 v[46:47], v[22:23], off
	v_lshlrev_b64 v[22:23], 7, v[56:57]
	v_and_b32_e32 v94, 15, v1
	v_lshl_add_u64 v[22:23], s[42:43], 0, v[22:23]
	s_addc_u32 s42, s97, 0
	s_lshl_b32 s27, s20, 4
	s_lshl_b32 s26, s20, 5
	v_or_b32_e32 v86, s24, v94
	s_add_u32 s74, s36, s26
	v_lshrrev_b32_e32 v2, 1, v1
	v_lshl_add_u64 v[22:23], v[22:23], 0, s[72:73]
	s_addc_u32 s75, s42, 0
	v_and_b32_e32 v2, 24, v2
	v_cmp_lt_i32_e32 vcc, 63, v86
	v_mov_b32_e32 v21, s37
	global_load_dword v57, v[22:23], off
	v_lshl_add_u64 v[22:23], s[74:75], 0, v[2:3]
	v_max_i32_e32 v2, 48, v86
	v_cndmask_b32_e32 v52, v230, v21, vcc
	v_or_b32_e32 v87, 16, v86
	v_add_u32_e32 v2, v52, v2
	v_cmp_lt_i32_e32 vcc, 63, v87
	v_mad_i64_i32 v[52:53], s[36:37], v2, s29, v[22:23]
	v_max_i32_e32 v2, 48, v87
	v_cndmask_b32_e32 v21, v230, v21, vcc
	v_add_u32_e32 v2, v21, v2
	v_mad_i64_i32 v[22:23], s[36:37], v2, s29, v[22:23]
	global_load_dwordx4 v[4:7], v[4:5], off
	s_cmp_lt_u32 s25, 64
	global_load_dwordx4 v[8:11], v[8:9], off
	s_cselect_b64 s[60:61], -1, 0
	s_sub_u32 s98, s25, 0x100
	s_cmp_lt_u32 s98, 64
	s_cselect_b64 s[98:99], -1, 0
	s_mov_b32 s100, 0x3fb8aa3b
	s_mov_b32 s101, 0x3fb8aa3b
	global_load_dwordx4 v[12:15], v[12:13], off
	v_cmp_lt_i32_e64 s[0:1], 11, v48
	global_load_dwordx4 v[16:19], v[16:17], off
	v_cmp_lt_i32_e64 s[40:41], 23, v49
	global_load_dwordx2 v[52:53], v[52:53], off
	s_and_b64 vcc, exec, s[60:61]
	global_load_dwordx2 v[84:85], v[22:23], off
	s_waitcnt lgkmcnt(0)
	s_barrier
	s_cbranch_vccz .LBB0_349
	v_cmp_lt_u32_e32 vcc, 47, v65
	v_mov_b32_e32 v21, v3
	s_waitcnt vmcnt(13)
	v_cndmask_b32_e32 v2, 0, v20, vcc
	v_mul_f32_e64 v20, v2, -v63
	s_nop 1
	v_mov_b32_dpp v21, v20 row_shr:1 row_mask:0xf bank_mask:0xf
	v_fma_f32 v20, v2, -v63, v21
	v_mov_b32_e32 v21, v3
	s_nop 0
	v_add_f32_dpp v20, v20, v20 row_shr:2 row_mask:0xf bank_mask:0xf bound_ctrl:1
	s_nop 1
	v_add_f32_dpp v20, v20, v20 row_shr:4 row_mask:0xf bank_mask:0xf bound_ctrl:1
	s_nop 1
	v_add_f32_dpp v20, v20, v20 row_shr:8 row_mask:0xf bank_mask:0xf bound_ctrl:1
	s_nop 1
	v_mov_b32_dpp v21, v20 row_bcast:15 row_mask:0xa bank_mask:0xf
	v_add_f32_e32 v20, v20, v21
	v_mov_b32_e32 v21, v3
	s_nop 1
	v_mov_b32_dpp v21, v20 row_bcast:31 row_mask:0xc bank_mask:0xf
	v_add_f32_e32 v20, v20, v21
	v_lshl_add_u32 v21, v65, 2, 0
	v_add_u32_e32 v22, 0x1a400, v21
	ds_write_b32 v22, v2
	v_add_u32_e32 v2, 0x1a600, v21
	ds_write_b32 v2, v20

.LBB0_360:
	v_add_u32_e32 v156, v106, v107
	ds_read_b128 v[160:163], v156 offset:34816
	ds_read_b128 v[164:167], v156 offset:34880
	ds_read_b128 v[168:171], v156 offset:17408
	ds_read_b128 v[172:175], v156 offset:17472
	ds_read_b128 v[176:179], v138
	ds_read_b128 v[180:183], v138 offset:64
	ds_read_b128 v[184:187], v138 offset:4352
	ds_read_b128 v[188:191], v138 offset:4416
	ds_read_b128 v[192:195], v156 offset:34944
	ds_read_b128 v[202:205], v156 offset:35008
	ds_read_b128 v[206:209], v156 offset:17536
	ds_read_b128 v[210:213], v156 offset:17600
	ds_read_b128 v[214:217], v138 offset:128
	ds_read_b128 v[236:239], v138 offset:192
	ds_read_b128 v[240:243], v138 offset:4480
	ds_read_b128 v[244:247], v138 offset:4544
	s_waitcnt lgkmcnt(11)
	v_mfma_f32_16x16x32_bf16 v[248:251], v[160:163], v[176:179], 0
	v_mfma_f32_16x16x32_bf16 v[176:179], v[168:171], v[176:179], 0
	s_waitcnt lgkmcnt(9)
	v_mfma_f32_16x16x32_bf16 v[160:163], v[160:163], v[184:187], 0
	v_mfma_f32_16x16x32_bf16 v[168:171], v[168:171], v[184:187], 0
	v_mfma_f32_16x16x32_bf16 v[184:187], v[164:167], v[180:183], v[248:251]
	v_mfma_f32_16x16x32_bf16 v[176:179], v[172:175], v[180:183], v[176:179]
	s_waitcnt lgkmcnt(8)
	v_mfma_f32_16x16x32_bf16 v[160:163], v[164:167], v[188:191], v[160:163]
	v_mfma_f32_16x16x32_bf16 v[164:167], v[172:175], v[188:191], v[168:171]
	s_waitcnt lgkmcnt(3)
	v_mfma_f32_16x16x32_bf16 v[168:171], v[192:195], v[214:217], v[184:187]
	v_mfma_f32_16x16x32_bf16 v[172:175], v[206:209], v[214:217], v[176:179]
	s_waitcnt lgkmcnt(1)
	v_mfma_f32_16x16x32_bf16 v[160:163], v[192:195], v[240:243], v[160:163]
	s_nop 0
	ds_read_b128 v[176:179], v139
	ds_read_b128 v[180:183], v140 offset:52224
	ds_read_b128 v[184:187], v141 offset:54528
	ds_read_b128 v[188:191], v142 offset:56832
	ds_read_b128 v[192:195], v143 offset:59136
	v_mfma_f32_16x16x32_bf16 v[164:167], v[206:209], v[240:243], v[164:167]
	s_waitcnt lgkmcnt(5)
	v_mfma_f32_16x16x32_bf16 v[160:163], v[202:205], v[244:247], v[160:163]
	v_mfma_f32_16x16x32_bf16 v[168:171], v[202:205], v[236:239], v[168:171]
	v_mfma_f32_16x16x32_bf16 v[172:175], v[210:213], v[236:239], v[172:175]
	v_mfma_f32_16x16x32_bf16 v[164:167], v[210:213], v[244:247], v[164:167]
	ds_read_b32 v55, v109
	ds_read_b128 v[202:205], v127
	s_waitcnt lgkmcnt(0)
	v_pk_add_f32 v[198:199], v[54:55], v[202:203] op_sel:[1,0] op_sel_hi:[1,1] neg_lo:[0,1] neg_hi:[0,1]
	v_pk_add_f32 v[222:223], v[54:55], v[204:205] op_sel:[1,0] op_sel_hi:[1,1] neg_lo:[0,1] neg_hi:[0,1]
	v_pk_mul_f32 v[198:199], v[198:199], s[100:101]
	v_pk_mul_f32 v[222:223], v[222:223], s[100:101]
	v_exp_f32_e32 v198, v198
	v_exp_f32_e32 v199, v199
	v_exp_f32_e32 v222, v222
	v_exp_f32_e32 v223, v223
	v_pk_mul_f32 v[198:199], v[172:173], v[198:199]
	v_pk_mul_f32 v[222:223], v[174:175], v[222:223]
	v_cndmask_b32_e64 v198, v198, 0, s[42:43]
	v_cndmask_b32_e64 v199, 0, v199, s[44:45]
	v_cndmask_b32_e64 v222, v222, 0, s[46:47]
	v_cndmask_b32_e64 v223, v223, 0, s[48:49]
	v_cvt_pk_bf16_f32 v172, v198, v199
	v_cvt_pk_bf16_f32 v173, v222, v223
	ds_write_b64 v144, v[172:173]
	ds_read_b32 v89, v110
	ds_read_b128 v[172:175], v127
	v_mul_f32_e32 v55, 0x3fb8aa3b, v55
	v_exp_f32_e32 v154, v55
	s_waitcnt lgkmcnt(0)
	v_mul_f32_e32 v55, 0x3fb8aa3b, v89
	v_pk_add_f32 v[198:199], v[88:89], v[172:173] op_sel:[1,0] op_sel_hi:[1,1] neg_lo:[0,1] neg_hi:[0,1]
	v_pk_add_f32 v[222:223], v[88:89], v[174:175] op_sel:[1,0] op_sel_hi:[1,1] neg_lo:[0,1] neg_hi:[0,1]
	v_pk_mul_f32 v[198:199], v[198:199], s[100:101]
	v_pk_mul_f32 v[222:223], v[222:223], s[100:101]
	v_exp_f32_e32 v198, v198
	v_exp_f32_e32 v199, v199
	v_exp_f32_e32 v222, v222
	v_exp_f32_e32 v223, v223
	v_exp_f32_e32 v206, v55
	v_pk_mul_f32 v[198:199], v[164:165], v[198:199]
	v_pk_mul_f32 v[222:223], v[166:167], v[222:223]
	v_cndmask_b32_e64 v198, v198, 0, s[50:51]
	v_cndmask_b32_e64 v199, 0, v199, s[52:53]
	v_cndmask_b32_e64 v222, v222, 0, s[54:55]
	v_cndmask_b32_e64 v223, v223, 0, s[56:57]
	v_cvt_pk_bf16_f32 v164, v198, v199
	v_cvt_pk_bf16_f32 v165, v222, v223
	ds_write_b64 v145, v[164:165]
	v_mul_f32_e32 v54, 0x3fb8aa3b, v54
	v_exp_f32_e32 v54, v54
	ds_read_b128 v[164:167], v146 offset:52224
	v_add_u32_e32 v159, v108, v111
	ds_read_b128 v[172:175], v159
	v_pk_mul_f32 v[50:51], v[50:51], v[54:55] op_sel_hi:[1,0]
	v_pk_mul_f32 v[48:49], v[48:49], v[54:55] op_sel_hi:[1,0]
	v_pk_mul_f32 v[42:43], v[42:43], v[54:55] op_sel_hi:[1,0]
	v_pk_mul_f32 v[40:41], v[40:41], v[54:55] op_sel_hi:[1,0]
	v_pk_mul_f32 v[46:47], v[46:47], v[54:55] op_sel_hi:[1,0]
	v_pk_mul_f32 v[44:45], v[44:45], v[54:55] op_sel_hi:[1,0]
	v_pk_mul_f32 v[38:39], v[38:39], v[54:55] op_sel_hi:[1,0]
	v_pk_mul_f32 v[36:37], v[36:37], v[54:55] op_sel_hi:[1,0]
	v_mfma_f32_16x16x32_bf16 v[48:51], v[180:183], v[176:179], v[48:51]
	v_add_u32_e32 v54, v112, v113
	v_mfma_f32_16x16x32_bf16 v[40:43], v[184:187], v[176:179], v[40:43]
	v_mfma_f32_16x16x32_bf16 v[44:47], v[188:191], v[176:179], v[44:47]
	v_mfma_f32_16x16x32_bf16 v[36:39], v[192:195], v[176:179], v[36:39]
	ds_read_b128 v[176:179], v147 offset:54528
	s_waitcnt lgkmcnt(1)
	v_mfma_f32_16x16x32_bf16 v[48:51], v[164:167], v[172:175], v[48:51]
	ds_read_b128 v[164:167], v148 offset:56832
	ds_read_b128 v[180:183], v149 offset:59136
	s_waitcnt lgkmcnt(0)
	s_barrier
	s_waitcnt lgkmcnt(2)
	v_mfma_f32_16x16x32_bf16 v[40:43], v[176:179], v[172:175], v[40:43]
	ds_read_b128 v[176:179], v54
	ds_read_b128 v[184:187], v150
	v_add_u32_e32 v54, v112, v111
	s_waitcnt lgkmcnt(3)
	v_mfma_f32_16x16x32_bf16 v[44:47], v[164:167], v[172:175], v[44:47]
	ds_read_b128 v[164:167], v150 offset:2304
	ds_read_b128 v[188:191], v150 offset:64
	ds_read_b128 v[192:195], v54
	ds_read_b128 v[202:205], v150 offset:2368
	s_waitcnt lgkmcnt(6)
	v_mfma_f32_16x16x32_bf16 v[36:39], v[180:183], v[172:175], v[36:39]
	v_mul_f32_e64 v170, v170, v154
	v_mul_f32_e64 v171, v171, v154
	v_pk_mul_f32 v[168:169], v[168:169], v[154:155] op_sel_hi:[1,0]
	v_pk_mul_f32 v[162:163], v[162:163], v[206:207] op_sel_hi:[1,0]
	v_pk_mul_f32 v[160:161], v[160:161], v[206:207] op_sel_hi:[1,0]
	s_waitcnt lgkmcnt(4)
	v_mfma_f32_16x16x32_bf16 v[168:171], v[176:179], v[184:187], v[168:171]
	v_cvt_pk_bf16_f32 v54, v48, v49
	v_cvt_pk_bf16_f32 v55, v50, v51
	v_cvt_pk_bf16_f32 v172, v40, v41
	v_cvt_pk_bf16_f32 v173, v42, v43
	v_add_u32_e32 v157, 0x8800, v151
	s_waitcnt lgkmcnt(3)
	v_mfma_f32_16x16x32_bf16 v[160:163], v[176:179], v[164:167], v[160:163]
	ds_write2_b64 v157, v[54:55], v[172:173] offset1:4
	v_cvt_pk_bf16_f32 v54, v44, v45
	v_cvt_pk_bf16_f32 v55, v46, v47
	s_waitcnt lgkmcnt(2)
	v_mfma_f32_16x16x32_bf16 v[164:167], v[192:195], v[188:191], v[168:171]
	v_cmp_lt_i32_e32 vcc, v225, v220
	v_lshl_add_u64 v[92:93], v[86:87], 0, v[92:93]
	s_nop 0
	v_cvt_pk_bf16_f32 v168, v36, v37
	v_cvt_pk_bf16_f32 v169, v38, v39
	ds_write2_b64 v157, v[54:55], v[168:169] offset0:8 offset1:12
	v_cndmask_b32_e32 v54, v218, v225, vcc
	v_lshlrev_b32_e32 v153, 2, v54
	s_waitcnt vmcnt(9)
	v_lshlrev_b32_e32 v54, 16, v52
	v_and_b32_e32 v55, 0xffff0000, v52
	v_mul_f32_e32 v52, 0xbfb8aa3b, v54
	v_exp_f32_e32 v52, v52
	v_mul_f32_e32 v89, 0xbfb8aa3b, v55
	v_exp_f32_e32 v89, v89
	ds_read_b64 v[168:169], v128
	v_add_f32_e32 v52, 1.0, v52
	v_rcp_f32_e32 v170, v52
	v_add_f32_e32 v52, 1.0, v89
	v_rcp_f32_e32 v171, v52
	s_waitcnt lgkmcnt(0)
	v_lshlrev_b32_e32 v172, 16, v168
	v_and_b32_e32 v173, 0xffff0000, v168
	v_pk_fma_f32 v[164:165], v[0:1], v[172:173], v[164:165]
	v_pk_mul_f32 v[54:55], v[170:171], v[54:55]
	v_lshlrev_b32_e32 v52, 16, v53
	v_pk_mul_f32 v[164:165], v[54:55], v[164:165]
	v_and_b32_e32 v53, 0xffff0000, v53
	v_mul_f32_e32 v54, 0xbfb8aa3b, v52
	v_exp_f32_e32 v89, v54
	v_mul_f32_e32 v54, 0xbfb8aa3b, v53
	v_exp_f32_e32 v154, v54
	v_lshlrev_b32_e32 v168, 16, v169
	v_add_f32_e32 v89, 1.0, v89
	v_rcp_f32_e32 v170, v89
	v_add_f32_e32 v89, 1.0, v154
	v_rcp_f32_e32 v171, v89
	v_and_b32_e32 v169, 0xffff0000, v169
	v_pk_fma_f32 v[166:167], v[0:1], v[168:169], v[166:167]
	v_pk_mul_f32 v[54:55], v[164:165], v[164:165]
	v_pk_mul_f32 v[52:53], v[170:171], v[52:53]
	v_add_f32_e32 v54, v54, v55
	v_pk_mul_f32 v[166:167], v[52:53], v[166:167]
	v_cmp_lt_i32_e32 vcc, v226, v220
	v_pk_mul_f32 v[52:53], v[166:167], v[166:167]
	s_nop 0
	v_add_f32_e32 v52, v52, v54
	v_add_f32_e32 v89, v53, v52
	ds_bpermute_b32 v168, v153, v89
	v_cndmask_b32_e32 v154, v218, v226, vcc
	v_lshlrev_b32_e32 v154, 2, v154
	v_mfma_f32_16x16x32_bf16 v[52:55], v[192:195], v[202:205], v[160:163]
	s_waitcnt lgkmcnt(0)
	v_add_f32_e32 v89, v89, v168
	s_nop 0
	ds_bpermute_b32 v160, v154, v89
	v_cvt_pk_bf16_f32 v162, v164, v165
	v_cvt_pk_bf16_f32 v163, v166, v167
	global_store_dwordx2 v[92:93], v[162:163], off
	s_and_saveexec_b64 s[0:1], s[58:59]
	s_cbranch_execz .LBB0_362
	s_waitcnt lgkmcnt(0)
	v_add_f32_e32 v89, v89, v160
	ds_write_b32 v114, v89

.LBB0_373:
	ds_read_b128 v[160:163], v156 offset:34816
	ds_read_b128 v[164:167], v156 offset:34880
	ds_read_b128 v[168:171], v156 offset:17408
	ds_read_b128 v[172:175], v156 offset:17472
	ds_read_b128 v[176:179], v138
	ds_read_b128 v[180:183], v138 offset:64
	ds_read_b128 v[184:187], v138 offset:4352
	ds_read_b128 v[188:191], v138 offset:4416
	ds_read_b128 v[192:195], v156 offset:34944
	ds_read_b128 v[202:205], v156 offset:35008
	ds_read_b128 v[206:209], v156 offset:17536
	ds_read_b128 v[210:213], v156 offset:17600
	ds_read_b128 v[214:217], v138 offset:128
	ds_read_b128 v[236:239], v138 offset:192
	ds_read_b128 v[240:243], v138 offset:4480
	ds_read_b128 v[244:247], v138 offset:4544
	s_waitcnt lgkmcnt(11)
	v_mfma_f32_16x16x32_bf16 v[248:251], v[160:163], v[176:179], 0
	v_mfma_f32_16x16x32_bf16 v[176:179], v[168:171], v[176:179], 0
	s_waitcnt lgkmcnt(9)
	v_mfma_f32_16x16x32_bf16 v[160:163], v[160:163], v[184:187], 0
	v_mfma_f32_16x16x32_bf16 v[168:171], v[168:171], v[184:187], 0
	v_mfma_f32_16x16x32_bf16 v[184:187], v[164:167], v[180:183], v[248:251]
	v_mfma_f32_16x16x32_bf16 v[176:179], v[172:175], v[180:183], v[176:179]
	s_waitcnt lgkmcnt(8)
	v_mfma_f32_16x16x32_bf16 v[160:163], v[164:167], v[188:191], v[160:163]
	v_mfma_f32_16x16x32_bf16 v[164:167], v[172:175], v[188:191], v[168:171]
	s_waitcnt lgkmcnt(3)
	v_mfma_f32_16x16x32_bf16 v[168:171], v[192:195], v[214:217], v[184:187]
	v_mfma_f32_16x16x32_bf16 v[172:175], v[206:209], v[214:217], v[176:179]
	s_waitcnt lgkmcnt(1)
	v_mfma_f32_16x16x32_bf16 v[160:163], v[192:195], v[240:243], v[160:163]
	s_nop 0
	ds_read_b128 v[176:179], v139
	ds_read_b128 v[180:183], v140 offset:52224
	ds_read_b128 v[184:187], v141 offset:54528
	ds_read_b128 v[188:191], v142 offset:56832
	ds_read_b128 v[192:195], v143 offset:59136
	v_mfma_f32_16x16x32_bf16 v[164:167], v[206:209], v[240:243], v[164:167]
	v_mfma_f32_16x16x32_bf16 v[168:171], v[202:205], v[236:239], v[168:171]
	v_mfma_f32_16x16x32_bf16 v[172:175], v[210:213], v[236:239], v[172:175]
	s_waitcnt lgkmcnt(5)
	v_mfma_f32_16x16x32_bf16 v[160:163], v[202:205], v[244:247], v[160:163]
	v_mfma_f32_16x16x32_bf16 v[164:167], v[210:213], v[244:247], v[164:167]
	ds_read_b32 v88, v120
	ds_read_b128 v[202:205], v131
	s_waitcnt lgkmcnt(0)
	v_pk_add_f32 v[198:199], v[88:89], v[202:203] op_sel:[0,0] op_sel_hi:[0,1] neg_lo:[0,1] neg_hi:[0,1]
	v_pk_add_f32 v[222:223], v[88:89], v[204:205] op_sel:[0,0] op_sel_hi:[0,1] neg_lo:[0,1] neg_hi:[0,1]
	v_pk_mul_f32 v[198:199], v[198:199], s[100:101]
	v_pk_mul_f32 v[222:223], v[222:223], s[100:101]
	v_exp_f32_e32 v198, v198
	v_exp_f32_e32 v199, v199
	v_exp_f32_e32 v222, v222
	v_exp_f32_e32 v223, v223
	v_pk_mul_f32 v[198:199], v[172:173], v[198:199]
	v_pk_mul_f32 v[222:223], v[174:175], v[222:223]
	v_cndmask_b32_e64 v198, v198, 0, s[42:43]
	v_cndmask_b32_e64 v199, 0, v199, s[44:45]
	v_cndmask_b32_e64 v222, v222, 0, s[46:47]
	v_cndmask_b32_e64 v223, v223, 0, s[48:49]
	v_cvt_pk_bf16_f32 v54, v198, v199
	v_cvt_pk_bf16_f32 v55, v222, v223
	ds_write_b64 v144, v[54:55]
	ds_read_b32 v55, v121
	ds_read_b128 v[172:175], v131
	v_mul_f32_e32 v54, 0x3fb8aa3b, v88
	v_exp_f32_e32 v54, v54
	s_waitcnt lgkmcnt(0)
	v_mul_f32_e32 v88, 0x3fb8aa3b, v55
	v_pk_add_f32 v[198:199], v[54:55], v[172:173] op_sel:[1,0] op_sel_hi:[1,1] neg_lo:[0,1] neg_hi:[0,1]
	v_pk_add_f32 v[222:223], v[54:55], v[174:175] op_sel:[1,0] op_sel_hi:[1,1] neg_lo:[0,1] neg_hi:[0,1]
	v_pk_mul_f32 v[198:199], v[198:199], s[100:101]
	v_pk_mul_f32 v[222:223], v[222:223], s[100:101]
	v_exp_f32_e32 v198, v198
	v_exp_f32_e32 v199, v199
	v_exp_f32_e32 v222, v222
	v_exp_f32_e32 v223, v223
	v_exp_f32_e32 v88, v88
	v_pk_mul_f32 v[198:199], v[164:165], v[198:199]
	v_pk_mul_f32 v[222:223], v[166:167], v[222:223]
	v_cndmask_b32_e64 v198, v198, 0, s[50:51]
	v_cndmask_b32_e64 v199, 0, v199, s[52:53]
	v_cndmask_b32_e64 v222, v222, 0, s[54:55]
	v_cndmask_b32_e64 v223, v223, 0, s[56:57]
	v_cvt_pk_bf16_f32 v164, v198, v199
	v_cvt_pk_bf16_f32 v165, v222, v223
	ds_write_b64 v145, v[164:165]
	v_mul_f32_e32 v2, 0x3fb8aa3b, v2
	v_exp_f32_e32 v2, v2
	ds_read_b128 v[164:167], v159
	ds_read_b128 v[172:175], v146 offset:52224
	v_add_u32_e32 v55, v122, v111
	v_pk_mul_f32 v[50:51], v[50:51], v[2:3] op_sel_hi:[1,0]
	v_pk_mul_f32 v[48:49], v[48:49], v[2:3] op_sel_hi:[1,0]
	v_pk_mul_f32 v[42:43], v[42:43], v[2:3] op_sel_hi:[1,0]
	v_pk_mul_f32 v[40:41], v[40:41], v[2:3] op_sel_hi:[1,0]
	v_mfma_f32_16x16x32_bf16 v[48:51], v[180:183], v[176:179], v[48:51]
	v_mul_f32_e64 v46, v46, v2
	v_mul_f32_e64 v47, v47, v2
	v_pk_mul_f32 v[44:45], v[44:45], v[2:3] op_sel_hi:[1,0]
	v_pk_mul_f32 v[38:39], v[38:39], v[2:3] op_sel_hi:[1,0]
	v_pk_mul_f32 v[36:37], v[36:37], v[2:3] op_sel_hi:[1,0]
	v_mfma_f32_16x16x32_bf16 v[40:43], v[184:187], v[176:179], v[40:43]
	v_add_u32_e32 v2, v122, v113
	v_mfma_f32_16x16x32_bf16 v[44:47], v[188:191], v[176:179], v[44:47]
	v_mfma_f32_16x16x32_bf16 v[36:39], v[192:195], v[176:179], v[36:39]
	ds_read_b128 v[176:179], v147 offset:54528
	ds_read_b128 v[180:183], v148 offset:56832
	s_waitcnt lgkmcnt(2)
	v_mfma_f32_16x16x32_bf16 v[48:51], v[172:175], v[164:167], v[48:51]
	ds_read_b128 v[172:175], v149 offset:59136
	s_waitcnt lgkmcnt(0)
	s_barrier
	s_waitcnt lgkmcnt(2)
	v_mfma_f32_16x16x32_bf16 v[40:43], v[176:179], v[164:167], v[40:43]
	ds_read_b128 v[176:179], v2
	ds_read_b128 v[184:187], v55
	s_waitcnt lgkmcnt(3)
	v_mfma_f32_16x16x32_bf16 v[44:47], v[180:183], v[164:167], v[44:47]
	ds_read_b128 v[180:183], v150
	ds_read_b128 v[188:191], v150 offset:64
	ds_read_b128 v[192:195], v150 offset:2304
	ds_read_b128 v[202:205], v150 offset:2368
	s_waitcnt lgkmcnt(6)
	v_mfma_f32_16x16x32_bf16 v[36:39], v[172:175], v[164:167], v[36:39]
	v_mul_f32_e64 v166, v170, v54
	v_mul_f32_e64 v167, v171, v54
	v_pk_mul_f32 v[164:165], v[168:169], v[54:55] op_sel_hi:[1,0]
	v_pk_mul_f32 v[162:163], v[162:163], v[88:89] op_sel_hi:[1,0]
	v_pk_mul_f32 v[160:161], v[160:161], v[88:89] op_sel_hi:[1,0]
	v_cvt_pk_bf16_f32 v54, v48, v49
	v_cvt_pk_bf16_f32 v55, v50, v51
	v_cvt_pk_bf16_f32 v88, v40, v41
	v_cvt_pk_bf16_f32 v89, v42, v43
	ds_write2_b64 v157, v[54:55], v[88:89] offset1:4
	v_cvt_pk_bf16_f32 v54, v44, v45
	v_cvt_pk_bf16_f32 v55, v46, v47
	v_cvt_pk_bf16_f32 v88, v36, v37
	v_cvt_pk_bf16_f32 v89, v38, v39
	ds_write2_b64 v157, v[54:55], v[88:89] offset0:8 offset1:12
	s_waitcnt vmcnt(9)
	v_lshlrev_b32_e32 v54, 16, v52
	v_and_b32_e32 v55, 0xffff0000, v52
	v_mul_f32_e32 v2, 0xbfb8aa3b, v54
	v_exp_f32_e32 v2, v2
	v_mul_f32_e32 v52, 0xbfb8aa3b, v55
	v_exp_f32_e32 v52, v52
	s_waitcnt lgkmcnt(5)
	v_mfma_f32_16x16x32_bf16 v[164:167], v[176:179], v[180:183], v[164:167]
	ds_read_b64 v[88:89], v132
	v_add_f32_e32 v2, 1.0, v2
	v_rcp_f32_e32 v156, v2
	v_add_f32_e32 v2, 1.0, v52
	s_waitcnt lgkmcnt(4)
	v_mfma_f32_16x16x32_bf16 v[158:161], v[176:179], v[192:195], v[160:163]
	v_rcp_f32_e32 v157, v2
	v_lshlrev_b32_e32 v52, 16, v53
	v_and_b32_e32 v53, 0xffff0000, v53
	v_mfma_f32_16x16x32_bf16 v[162:165], v[184:187], v[188:191], v[164:167]
	v_mul_f32_e64 v54, v156, v54
	v_mul_f32_e64 v55, v157, v55
	v_mul_f32_e32 v2, 0xbfb8aa3b, v52
	v_exp_f32_e32 v2, v2
	s_waitcnt lgkmcnt(0)
	v_lshlrev_b32_e32 v166, 16, v88
	v_and_b32_e32 v167, 0xffff0000, v88
	s_nop 0
	v_pk_fma_f32 v[162:163], v[0:1], v[166:167], v[162:163]
	v_add_f32_e32 v2, 1.0, v2
	v_pk_mul_f32 v[156:157], v[54:55], v[162:163]
	v_mul_f32_e32 v54, 0xbfb8aa3b, v53
	v_exp_f32_e32 v88, v54
	v_rcp_f32_e32 v162, v2
	v_pk_mul_f32 v[54:55], v[156:157], v[156:157]
	v_cvt_pk_bf16_f32 v156, v156, v157
	v_add_f32_e32 v2, 1.0, v88
	v_rcp_f32_e32 v163, v2
	v_lshlrev_b32_e32 v88, 16, v89
	v_and_b32_e32 v89, 0xffff0000, v89
	v_pk_fma_f32 v[88:89], v[0:1], v[88:89], v[164:165]
	v_pk_mul_f32 v[52:53], v[162:163], v[52:53]
	v_add_f32_e32 v2, v54, v55
	v_pk_mul_f32 v[162:163], v[52:53], v[88:89]
	v_lshl_add_u64 v[92:93], v[86:87], 0, v[92:93]
	v_pk_mul_f32 v[52:53], v[162:163], v[162:163]
	v_cvt_pk_bf16_f32 v157, v162, v163
	v_add_f32_e32 v2, v52, v2
	v_add_f32_e32 v2, v53, v2
	ds_bpermute_b32 v88, v153, v2
	v_mfma_f32_16x16x32_bf16 v[52:55], v[184:187], v[202:205], v[158:161]
	global_store_dwordx2 v[92:93], v[156:157], off
	s_waitcnt lgkmcnt(0)
	v_add_f32_e32 v2, v2, v88
	ds_bpermute_b32 v88, v154, v2
	s_and_saveexec_b64 s[0:1], s[58:59]
	s_cbranch_execz .LBB0_375
	s_waitcnt lgkmcnt(0)
	v_add_f32_e32 v2, v2, v88
	ds_write_b32 v114, v2

	.amdhsa_kernel _Z10fwd_kernel6Params
		.amdhsa_group_segment_fixed_size 0
		.amdhsa_private_segment_fixed_size 0
		.amdhsa_kernarg_size 448
		.amdhsa_user_sgpr_count 2
		.amdhsa_user_sgpr_dispatch_ptr 0
		.amdhsa_user_sgpr_queue_ptr 0
		.amdhsa_user_sgpr_kernarg_segment_ptr 1
		.amdhsa_user_sgpr_dispatch_id 0
		.amdhsa_user_sgpr_kernarg_preload_length 0
		.amdhsa_user_sgpr_kernarg_preload_offset 0
		.amdhsa_user_sgpr_private_segment_size 0
		.amdhsa_uses_dynamic_stack 0
		.amdhsa_enable_private_segment 0
		.amdhsa_system_sgpr_workgroup_id_x 1
		.amdhsa_system_sgpr_workgroup_id_y 0
		.amdhsa_system_sgpr_workgroup_id_z 0
		.amdhsa_system_sgpr_workgroup_info 0
		.amdhsa_system_vgpr_workitem_id 2
		.amdhsa_next_free_vgpr 256
		.amdhsa_next_free_sgpr 102
		.amdhsa_accum_offset 256
		.amdhsa_reserve_vcc 1
		.amdhsa_float_round_mode_32 0
		.amdhsa_float_round_mode_16_64 0
		.amdhsa_float_denorm_mode_32 3
		.amdhsa_float_denorm_mode_16_64 3
		.amdhsa_dx10_clamp 1
		.amdhsa_ieee_mode 1
		.amdhsa_fp16_overflow 0
		.amdhsa_tg_split 0
		.amdhsa_exception_fp_ieee_invalid_op 0
		.amdhsa_exception_fp_denorm_src 0
		.amdhsa_exception_fp_ieee_div_zero 0
		.amdhsa_exception_fp_ieee_overflow 0
		.amdhsa_exception_fp_ieee_underflow 0
		.amdhsa_exception_fp_ieee_inexact 0
		.amdhsa_exception_int_div_zero 0
	.end_amdhsa_kernel

amdhsa.kernels:
  - .agpr_count:     0
    .args:
      - .offset:         0
        .size:           192
        .value_kind:     by_value
      - .offset:         192
        .size:           4
        .value_kind:     hidden_block_count_x
      - .offset:         196
        .size:           4
        .value_kind:     hidden_block_count_y
      - .offset:         200
        .size:           4
        .value_kind:     hidden_block_count_z
      - .offset:         204
        .size:           2
        .value_kind:     hidden_group_size_x
      - .offset:         206
        .size:           2
        .value_kind:     hidden_group_size_y
      - .offset:         208
        .size:           2
        .value_kind:     hidden_group_size_z
      - .offset:         210
        .size:           2
        .value_kind:     hidden_remainder_x
      - .offset:         212
        .size:           2
        .value_kind:     hidden_remainder_y
      - .offset:         214
        .size:           2
        .value_kind:     hidden_remainder_z
      - .offset:         232
        .size:           8
        .value_kind:     hidden_global_offset_x
      - .offset:         240
        .size:           8
        .value_kind:     hidden_global_offset_y
      - .offset:         248
        .size:           8
        .value_kind:     hidden_global_offset_z
      - .offset:         256
        .size:           2
        .value_kind:     hidden_grid_dims
      - .offset:         280
        .size:           8
        .value_kind:     hidden_multigrid_sync_arg
      - .offset:         312
        .size:           4
        .value_kind:     hidden_dynamic_lds_size
    .group_segment_fixed_size: 0
    .kernarg_segment_align: 8
    .kernarg_segment_size: 448
    .language:       OpenCL C
    .language_version:
      - 2
      - 0
    .max_flat_workgroup_size: 512
    .name:           _Z10fwd_kernel6Params
    .private_segment_fixed_size: 0
    .sgpr_count:     108
    .sgpr_spill_count: 200
    .symbol:         _Z10fwd_kernel6Params.kd
    .uniform_work_group_size: 1
    .uses_dynamic_stack: false
    .vgpr_count:     256
    .vgpr_spill_count: 0
    .wavefront_size: 64
